# rms rewrite padded by 12 bytes so every later loop head keeps the placement (mod 64 B) it has in the baseline
# baseline (speedup 1.0000x reference)
.Lrms_jn_2:
	s_mov_b32 s3, s21
	s_cmpk_lt_i32 s3, 0x4800
	s_cbranch_scc1 .Lrms_loop
	s_nop 0
	s_nop 0
	s_nop 0
